# peeled first K-iteration also relaxes vmcnt (24/24/40) in P1,P6,P8 so it does not wait on the previous epilogue's stores
# speedup vs baseline: 1.0002x; 1.0002x over previous
;     DI bool next(int i, Unit& u) const { if (!s.next(i >> 1, u)) return false; u.sel = i & 1; return true; }
; #define PG8_WAIT_V(n) asm volatile("s_waitcnt vmcnt(" #n ")" ::: "memory")
; template <class Epi, class Sched, bool ALIGN_EPI, bool CONVA>
; DI void gemm_phase(LAS unsigned char* lds, const Gemm g, const Sched& S, const Epi& E) {
;     const int tid = threadIdx.x, wid = __builtin_amdgcn_readfirstlane(tid >> 6), lane = tid & 63, wr = wid >> 2, wc = wid & 3, fr = lane & 15, fq = lane >> 4;
;     const int K = g.K; const int nt = g.ntk ? g.ntk : K / BK;
;     unsigned voffA[2], voffB[2];
; #pragma unroll
;     for (int i = 0; i < 2; ++i) { int R, C; stage_rc(tid * 16 + i * 8192, R, C); const int Rb = Epi::PERM ? ((R & ~31) + perm32(R & 31)) : R;
;         const int Ra = CONVA ? (128 * (R >> 6) + 8 * (R & 15) + ((R >> 4) & 3)) : R;
;         voffA[i] = (unsigned)(Ra * K + C) * 2u; voffB[i] = (unsigned)(Rb * K + C) * 2u; }
;     const size_t kstep = (size_t)(BK * 2);
;     const size_t hstepB = (size_t)HALF * K * 2, tstepB = 2 * hstepB;
;     const size_t hstepA = CONVA ? (size_t)4 * K * 2 : hstepB, tstepA = CONVA ? (size_t)254 * K * 2 : tstepB;
;     const long abias = CONVA ? -(long)K * 2 : 0;
;     const unsigned ldsw = (unsigned)wid * 1024u;
;     const int aoff = lds_byte(wr * 64 + fr, fq * 8), boff = lds_byte(wc * 32 + fr, fq * 8);
;     ...
;     Unit cur, nxt; int ui = 0;
;     if (!S.next(0, cur)) return;
;     f32x4 acc[2][2][4][2];
; #pragma unroll
;     for (int a = 0; a < 2; ++a)
; #pragma unroll
;         for (int b = 0; b < 2; ++b)
; #pragma unroll
;             for (int m = 0; m < 4; ++m)
; #pragma unroll
;                 for (int n = 0; n < 2; ++n) acc[a][b][m][n] = (f32x4){0.f, 0.f, 0.f, 0.f};
;     bf16x8 At[4][2], B0[2][2], B1[2][2];
;     const char* cA = (const char*)(cur.sel ? g.A2 : g.A) + (size_t)cur.pm * tstepA + abias; const char* cB = (const char*)(cur.sel ? g.Bt2 : g.Bt) + (size_t)cur.pn * tstepB;
;     PG8_STAGE(PG8_SB(0, 0), cB, voffB); PG8_STAGE(PG8_SB(0, 1), cB + hstepB, voffB); PG8_STAGE(PG8_SA(0, 0), cA, voffA); PG8_STAGE(PG8_SA(0, 1), cA + hstepA, voffA);
;     if (wr == 1) PG8_BAR;
;     PG8_WAIT_V(2); PG8_BAR;
;     PG8_STAGE(PG8_SB(1, 0), cB + kstep, voffB); PG8_STAGE(PG8_SA(1, 0), cA + kstep, voffA); PG8_STAGE(PG8_SB(1, 1), cB + hstepB + kstep, voffB);
;     PG8_WAIT_V(6); PG8_BAR;
.LBB0_156:
	s_lshl_b32 s6, s6, 5
	s_and_b32 s30, s6, 0x60
	s_mov_b64 s[6:7], 0x80
	s_add_i32 m0, s35, 0x18000
	v_lshl_add_u64 v[6:7], v[6:7], 0, s[6:7]
	s_lshl_b32 s9, s8, 13
	s_lshl_b32 s12, s30, 7
	s_waitcnt vmcnt(2)
	s_barrier
	global_load_lds_dwordx4 v[6:7], off
	v_lshl_add_u64 v[4:5], v[4:5], 0, s[6:7]
	s_add_i32 m0, s35, 0x1a000
	s_add_i32 s62, s35, 0x8000
	s_add_i32 s63, s35, 0xa000
	global_load_lds_dwordx4 v[4:5], off
	v_lshl_add_u64 v[0:1], v[0:1], 0, s[6:7]
	s_mov_b32 m0, s62
	s_add_u32 s10, s52, 0x40080
	global_load_lds_dwordx4 v[0:1], off
	v_lshl_add_u64 v[0:1], v[2:3], 0, s[6:7]
	s_mov_b32 m0, s63
	s_addc_u32 s11, s53, 0
	global_load_lds_dwordx4 v[0:1], off
	s_add_i32 m0, s35, 0x1c000
	v_lshl_add_u64 v[0:1], s[10:11], 0, v[132:133]
	global_load_lds_dwordx4 v[0:1], off
	v_lshl_add_u64 v[0:1], s[10:11], 0, v[128:129]
	s_add_i32 m0, s35, 0x1e000
	v_lshlrev_b32_e32 v2, 2, v176
	global_load_lds_dwordx4 v[0:1], off
	v_and_b32_e32 v0, 15, v176
	v_lshlrev_b32_e32 v1, 1, v11
	v_lshl_or_b32 v146, s8, 6, v0
	v_lshl_or_b32 v0, v0, 6, v1
	v_and_b32_e32 v2, 32, v2
	s_cmpk_lt_u32 s1, 0x100
	v_readlane_b32 s40, v252, 22
	s_sext_i32_i8 s69, s0
	v_bitop3_b32 v0, v0, s9, v2 bitop3:0xde
	v_lshlrev_b32_e32 v3, 6, v176
	s_movk_i32 s0, 0x3c0
	s_cselect_b64 s[8:9], -1, 0
	v_readlane_b32 s41, v252, 23
	s_add_u32 s10, s40, 0x1f800000
	v_and_or_b32 v1, v3, s0, v1
	s_addc_u32 s11, s41, 0
	v_bitop3_b32 v147, s12, v1, v2 bitop3:0xf6
	s_add_u32 s12, s40, 0x1d000000
	s_addc_u32 s13, s41, 0
	s_add_u32 s18, s40, 0x2c000000
	v_lshlrev_b32_e32 v1, 8, v176
	s_addc_u32 s19, s41, 0
	v_and_b32_e32 v1, 0x38000, v1
	v_lshlrev_b32_e32 v2, 11, v12
	s_add_u32 s20, s40, 0x18000000
	v_or3_b32 v1, v9, v1, v2
	s_addc_u32 s21, s41, 0
	v_add_u32_e32 v138, v1, v10
	v_lshlrev_b32_e32 v1, 4, v8
	s_waitcnt vmcnt(0)
	s_add_u32 s64, s40, 0x4000000
	v_and_b32_e32 v1, 0x78000, v1
	s_addc_u32 s65, s41, 0
	v_or3_b32 v1, v9, v1, v2
	s_add_i32 s67, 0, 0x10000
	s_add_i32 s68, 0, 0x14000
	v_or_b32_e32 v148, s30, v11
	s_ashr_i32 s66, s76, 31
	v_mov_b32_e32 v139, v137
	v_add_u32_e32 v140, v1, v10
	v_mov_b32_e32 v141, v137
	v_mov_b64_e32 v[142:143], 0xf00
	v_mov_b64_e32 v[144:145], 0xeff
	v_add_u32_e32 v149, s67, v147
	v_add_u32_e32 v150, s68, v147
	v_add_u32_e32 v151, 0, v0
	s_barrier
	v_readlane_b32 s42, v252, 24
	v_readlane_b32 s43, v252, 25
	s_branch .LBB0_159

;     DI bool next(int i, Unit& u) const { if (!s.next(i >> 1, u)) return false; u.sel = i & 1; return true; }
; template <class Epi, class Sched, bool ALIGN_EPI, bool CONVA>
; DI void gemm_phase(LAS unsigned char* lds, const Gemm g, const Sched& S, const Epi& E) {
;     ...
;         const bool has_next = S.next(ui + 1, nxt);
;         const char* nA = has_next ? (const char*)(nxt.sel ? g.A2 : g.A) + (size_t)nxt.pm * tstepA + abias : cA;
;         const char* nB = has_next ? (const char*)(nxt.sel ? g.Bt2 : g.Bt) + (size_t)nxt.pn * tstepB : cB;
.LBB0_161:
	s_ashr_i32 s41, s40, 31
	s_lshl_b64 s[42:43], s[40:41], 19
	s_add_u32 s42, s28, s42
	s_addc_u32 s43, s29, s43
	s_and_b64 s[44:45], s[0:1], exec
	s_cselect_b32 s41, s43, s47
	s_cselect_b32 s70, s42, s46
	s_ashr_i32 s31, s30, 31
	s_lshl_b64 s[44:45], s[30:31], 19
	s_add_u32 s44, s14, s44
	s_addc_u32 s45, s15, s45
	s_and_b64 s[54:55], s[0:1], exec
	s_cselect_b32 s31, s45, s53
	s_cselect_b32 s71, s44, s52
	s_add_u32 s46, s46, 0x40080
	s_addc_u32 s47, s47, 0
	s_add_u32 s77, s52, 0x100
	s_addc_u32 s78, s53, 0
	s_mov_b32 s79, -2
	ds_read_b128 v[154:157], v149
	ds_read_b128 v[158:161], v149 offset:1024
	ds_read_b128 v[162:165], v149 offset:2048
	ds_read_b128 v[166:169], v149 offset:3072
	ds_read_b128 v[170:173], v150
	ds_read_b128 v[178:181], v150 offset:1024
	ds_read_b128 v[182:185], v150 offset:2048
	ds_read_b128 v[186:189], v150 offset:3072
	s_add_u32 s52, s46, 0xfffc0080
	s_addc_u32 s53, s47, -1
	s_cmp_eq_u32 s79, 12
	s_cselect_b32 s55, s41, s53
	s_cselect_b32 s54, s70, s52
	s_cselect_b32 s53, s31, s78
	s_cselect_b32 s52, s71, s77
	v_lshl_add_u64 v[174:175], s[46:47], 0, v[138:139]
	s_add_i32 m0, s35, 0xc000
	ds_read_b128 v[190:193], v151
	ds_read_b128 v[194:197], v151 offset:1024
	ds_read_b128 v[198:201], v151 offset:2048
	ds_read_b128 v[202:205], v151 offset:3072
	ds_read_b128 v[206:209], v151 offset:4096
	ds_read_b128 v[214:217], v151 offset:5120
	ds_read_b128 v[218:221], v151 offset:6144
	ds_read_b128 v[222:225], v151 offset:7168
	global_load_lds_dwordx4 v[174:175], off
	v_lshl_add_u64 v[174:175], s[46:47], 0, v[140:141]
	s_add_i32 m0, s35, 0xe000
	s_nop 0
	global_load_lds_dwordx4 v[174:175], off
	s_waitcnt vmcnt(24)
	s_waitcnt lgkmcnt(0)
	s_barrier
	s_setprio 1
	s_waitcnt lgkmcnt(0)
	v_mfma_f32_16x16x32_bf16 v[124:127], v[154:157], v[190:193], 0
	v_mfma_f32_16x16x32_bf16 v[120:123], v[162:165], v[190:193], 0
	v_mfma_f32_16x16x32_bf16 v[116:119], v[154:157], v[198:201], 0
	v_mfma_f32_16x16x32_bf16 v[112:115], v[162:165], v[198:201], 0
	v_mfma_f32_16x16x32_bf16 v[100:103], v[154:157], v[206:209], 0
	v_mfma_f32_16x16x32_bf16 v[96:99], v[162:165], v[206:209], 0
	v_mfma_f32_16x16x32_bf16 v[84:87], v[154:157], v[218:221], 0
	v_mfma_f32_16x16x32_bf16 v[80:83], v[162:165], v[218:221], 0
	v_mfma_f32_16x16x32_bf16 v[124:127], v[158:161], v[194:197], v[124:127]
	v_mfma_f32_16x16x32_bf16 v[120:123], v[166:169], v[194:197], v[120:123]
	v_mfma_f32_16x16x32_bf16 v[116:119], v[158:161], v[202:205], v[116:119]
	v_mfma_f32_16x16x32_bf16 v[112:115], v[166:169], v[202:205], v[112:115]
	v_mfma_f32_16x16x32_bf16 v[100:103], v[158:161], v[214:217], v[100:103]
	v_mfma_f32_16x16x32_bf16 v[96:99], v[166:169], v[214:217], v[96:99]
	v_mfma_f32_16x16x32_bf16 v[84:87], v[158:161], v[222:225], v[84:87]
	v_mfma_f32_16x16x32_bf16 v[80:83], v[166:169], v[222:225], v[80:83]
	s_setprio 0
	s_setprio 1
	v_mfma_f32_16x16x32_bf16 v[108:111], v[170:173], v[190:193], 0
	v_mfma_f32_16x16x32_bf16 v[104:107], v[182:185], v[190:193], 0
	v_mfma_f32_16x16x32_bf16 v[92:95], v[170:173], v[198:201], 0
	v_mfma_f32_16x16x32_bf16 v[88:91], v[182:185], v[198:201], 0
	v_mfma_f32_16x16x32_bf16 v[76:79], v[170:173], v[206:209], 0
	v_mfma_f32_16x16x32_bf16 v[72:75], v[182:185], v[206:209], 0
	v_mfma_f32_16x16x32_bf16 v[68:71], v[170:173], v[218:221], 0
	v_mfma_f32_16x16x32_bf16 v[64:67], v[182:185], v[218:221], 0
	v_mfma_f32_16x16x32_bf16 v[108:111], v[178:181], v[194:197], v[108:111]
	v_mfma_f32_16x16x32_bf16 v[104:107], v[186:189], v[194:197], v[104:107]
	v_mfma_f32_16x16x32_bf16 v[92:95], v[178:181], v[202:205], v[92:95]
	v_mfma_f32_16x16x32_bf16 v[88:91], v[186:189], v[202:205], v[88:91]
	v_mfma_f32_16x16x32_bf16 v[76:79], v[178:181], v[214:217], v[76:79]
	v_mfma_f32_16x16x32_bf16 v[72:75], v[186:189], v[214:217], v[72:75]
	v_mfma_f32_16x16x32_bf16 v[68:71], v[178:181], v[222:225], v[68:71]
	v_mfma_f32_16x16x32_bf16 v[64:67], v[186:189], v[222:225], v[64:67]
	s_setprio 0
	s_barrier
	s_add_i32 s80, s67, s33
	v_lshl_add_u64 v[174:175], s[52:53], 0, v[132:133]
	s_mov_b32 m0, s80
	ds_read_b128 v[190:193], v151 offset:16384
	ds_read_b128 v[194:197], v151 offset:17408
	ds_read_b128 v[198:201], v151 offset:18432
	ds_read_b128 v[202:205], v151 offset:19456
	ds_read_b128 v[206:209], v151 offset:20480
	ds_read_b128 v[214:217], v151 offset:21504
	ds_read_b128 v[218:221], v151 offset:22528
	ds_read_b128 v[222:225], v151 offset:23552
	global_load_lds_dwordx4 v[174:175], off
	s_add_i32 m0, s80, 0x2000
	s_add_u32 s80, s52, 0x40000
	v_lshl_add_u64 v[210:211], s[52:53], 0, v[128:129]
	s_addc_u32 s81, s53, 0
	s_add_i32 s83, s68, s33
	global_load_lds_dwordx4 v[210:211], off
	v_lshl_add_u64 v[226:227], s[80:81], 0, v[132:133]
	s_mov_b32 m0, s83
	v_lshl_add_u64 v[228:229], s[54:55], 0, v[130:131]
	global_load_lds_dwordx4 v[226:227], off
	v_lshl_add_u64 v[226:227], s[80:81], 0, v[128:129]
	s_add_i32 m0, s83, 0x2000
	s_nop 0
	global_load_lds_dwordx4 v[226:227], off
	v_lshl_add_u64 v[226:227], s[54:55], 0, v[134:135]
	s_mov_b32 m0, s35
	s_nop 0
	global_load_lds_dwordx4 v[226:227], off
	s_mov_b32 m0, s58
	s_nop 0
	global_load_lds_dwordx4 v[228:229], off
	s_waitcnt vmcnt(24)
	s_waitcnt lgkmcnt(0)
	s_barrier
	s_setprio 1
	s_waitcnt lgkmcnt(0)
	v_mfma_f32_16x16x32_bf16 v[60:63], v[154:157], v[190:193], 0
	v_mfma_f32_16x16x32_bf16 v[56:59], v[162:165], v[190:193], 0
	v_mfma_f32_16x16x32_bf16 v[52:55], v[154:157], v[198:201], 0
	v_mfma_f32_16x16x32_bf16 v[48:51], v[162:165], v[198:201], 0
	v_mfma_f32_16x16x32_bf16 v[36:39], v[154:157], v[206:209], 0
	v_mfma_f32_16x16x32_bf16 v[32:35], v[162:165], v[206:209], 0
	v_mfma_f32_16x16x32_bf16 v[20:23], v[154:157], v[218:221], 0
	v_mfma_f32_16x16x32_bf16 v[16:19], v[162:165], v[218:221], 0
	v_mfma_f32_16x16x32_bf16 v[60:63], v[158:161], v[194:197], v[60:63]
	v_mfma_f32_16x16x32_bf16 v[56:59], v[166:169], v[194:197], v[56:59]
	v_mfma_f32_16x16x32_bf16 v[52:55], v[158:161], v[202:205], v[52:55]
	v_mfma_f32_16x16x32_bf16 v[48:51], v[166:169], v[202:205], v[48:51]
	v_mfma_f32_16x16x32_bf16 v[36:39], v[158:161], v[214:217], v[36:39]
	v_mfma_f32_16x16x32_bf16 v[32:35], v[166:169], v[214:217], v[32:35]
	v_mfma_f32_16x16x32_bf16 v[20:23], v[158:161], v[222:225], v[20:23]
	v_mfma_f32_16x16x32_bf16 v[16:19], v[166:169], v[222:225], v[16:19]
	s_setprio 0
	s_setprio 1
	v_mfma_f32_16x16x32_bf16 v[44:47], v[170:173], v[190:193], 0
	v_mfma_f32_16x16x32_bf16 v[40:43], v[182:185], v[190:193], 0
	v_mfma_f32_16x16x32_bf16 v[28:31], v[170:173], v[198:201], 0
	v_mfma_f32_16x16x32_bf16 v[24:27], v[182:185], v[198:201], 0
	v_mfma_f32_16x16x32_bf16 v[12:15], v[170:173], v[206:209], 0
	v_mfma_f32_16x16x32_bf16 v[8:11], v[182:185], v[206:209], 0
	v_mfma_f32_16x16x32_bf16 v[4:7], v[170:173], v[218:221], 0
	v_mfma_f32_16x16x32_bf16 v[0:3], v[182:185], v[218:221], 0
	v_mfma_f32_16x16x32_bf16 v[44:47], v[178:181], v[194:197], v[44:47]
	v_mfma_f32_16x16x32_bf16 v[40:43], v[186:189], v[194:197], v[40:43]
	v_mfma_f32_16x16x32_bf16 v[28:31], v[178:181], v[202:205], v[28:31]
	v_mfma_f32_16x16x32_bf16 v[24:27], v[186:189], v[202:205], v[24:27]
	v_mfma_f32_16x16x32_bf16 v[12:15], v[178:181], v[214:217], v[12:15]
	v_mfma_f32_16x16x32_bf16 v[8:11], v[186:189], v[214:217], v[8:11]
	v_mfma_f32_16x16x32_bf16 v[4:7], v[178:181], v[222:225], v[4:7]
	v_mfma_f32_16x16x32_bf16 v[0:3], v[186:189], v[222:225], v[0:3]
	s_setprio 0
	s_barrier
	s_add_i32 s80, 0, 0x18000
	v_add_u32_e32 v136, s80, v147
	s_add_i32 s81, 0, 0x1c000
	ds_read_b128 v[154:157], v136
	ds_read_b128 v[158:161], v136 offset:1024
	ds_read_b128 v[162:165], v136 offset:2048
	ds_read_b128 v[166:169], v136 offset:3072
	v_add_u32_e32 v136, s81, v147
	ds_read_b128 v[170:173], v136
	ds_read_b128 v[178:181], v136 offset:1024
	ds_read_b128 v[182:185], v136 offset:2048
	ds_read_b128 v[186:189], v136 offset:3072
	s_add_u32 s54, s54, 0x40000
	s_addc_u32 s55, s55, 0
	s_mov_b32 m0, s59
	v_lshl_add_u64 v[230:231], s[54:55], 0, v[134:135]
	ds_read_b128 v[190:193], v151 offset:32768
	ds_read_b128 v[194:197], v151 offset:33792
	ds_read_b128 v[198:201], v151 offset:34816
	ds_read_b128 v[202:205], v151 offset:35840
	ds_read_b128 v[206:209], v151 offset:36864
	ds_read_b128 v[214:217], v151 offset:37888
	ds_read_b128 v[218:221], v151 offset:38912
	ds_read_b128 v[222:225], v151 offset:39936
	global_load_lds_dwordx4 v[230:231], off
	v_lshl_add_u64 v[230:231], s[54:55], 0, v[130:131]
	s_mov_b32 m0, s60
	s_nop 0
	global_load_lds_dwordx4 v[230:231], off
	s_waitcnt vmcnt(8)
	s_waitcnt lgkmcnt(0)
	s_barrier
	s_setprio 1
	s_waitcnt lgkmcnt(0)
	v_mfma_f32_16x16x32_bf16 v[124:127], v[154:157], v[190:193], v[124:127]
	v_mfma_f32_16x16x32_bf16 v[120:123], v[162:165], v[190:193], v[120:123]
	v_mfma_f32_16x16x32_bf16 v[116:119], v[154:157], v[198:201], v[116:119]
	v_mfma_f32_16x16x32_bf16 v[112:115], v[162:165], v[198:201], v[112:115]
	v_mfma_f32_16x16x32_bf16 v[100:103], v[154:157], v[206:209], v[100:103]
	v_mfma_f32_16x16x32_bf16 v[96:99], v[162:165], v[206:209], v[96:99]
	v_mfma_f32_16x16x32_bf16 v[84:87], v[154:157], v[218:221], v[84:87]
	v_mfma_f32_16x16x32_bf16 v[80:83], v[162:165], v[218:221], v[80:83]
	v_mfma_f32_16x16x32_bf16 v[124:127], v[158:161], v[194:197], v[124:127]
	v_mfma_f32_16x16x32_bf16 v[120:123], v[166:169], v[194:197], v[120:123]
	v_mfma_f32_16x16x32_bf16 v[116:119], v[158:161], v[202:205], v[116:119]
	v_mfma_f32_16x16x32_bf16 v[112:115], v[166:169], v[202:205], v[112:115]
	v_mfma_f32_16x16x32_bf16 v[100:103], v[158:161], v[214:217], v[100:103]
	v_mfma_f32_16x16x32_bf16 v[96:99], v[166:169], v[214:217], v[96:99]
	v_mfma_f32_16x16x32_bf16 v[84:87], v[158:161], v[222:225], v[84:87]
	v_mfma_f32_16x16x32_bf16 v[80:83], v[166:169], v[222:225], v[80:83]
	s_setprio 0
	s_setprio 1
	v_mfma_f32_16x16x32_bf16 v[108:111], v[170:173], v[190:193], v[108:111]
	v_mfma_f32_16x16x32_bf16 v[104:107], v[182:185], v[190:193], v[104:107]
	v_mfma_f32_16x16x32_bf16 v[92:95], v[170:173], v[198:201], v[92:95]
	v_mfma_f32_16x16x32_bf16 v[88:91], v[182:185], v[198:201], v[88:91]
	v_mfma_f32_16x16x32_bf16 v[76:79], v[170:173], v[206:209], v[76:79]
	v_mfma_f32_16x16x32_bf16 v[72:75], v[182:185], v[206:209], v[72:75]
	v_mfma_f32_16x16x32_bf16 v[68:71], v[170:173], v[218:221], v[68:71]
	v_mfma_f32_16x16x32_bf16 v[64:67], v[182:185], v[218:221], v[64:67]
	v_mfma_f32_16x16x32_bf16 v[108:111], v[178:181], v[194:197], v[108:111]
	v_mfma_f32_16x16x32_bf16 v[104:107], v[186:189], v[194:197], v[104:107]
	v_mfma_f32_16x16x32_bf16 v[92:95], v[178:181], v[202:205], v[92:95]
	v_mfma_f32_16x16x32_bf16 v[88:91], v[186:189], v[202:205], v[88:91]
	v_mfma_f32_16x16x32_bf16 v[76:79], v[178:181], v[214:217], v[76:79]
	v_mfma_f32_16x16x32_bf16 v[72:75], v[186:189], v[214:217], v[72:75]
	v_mfma_f32_16x16x32_bf16 v[68:71], v[178:181], v[222:225], v[68:71]
	v_mfma_f32_16x16x32_bf16 v[64:67], v[186:189], v[222:225], v[64:67]
	s_setprio 0
	s_barrier
; #define PG8_WAIT_V(n) asm volatile("s_waitcnt vmcnt(" #n ")" ::: "memory")
; template <class Epi, class Sched, bool ALIGN_EPI, bool CONVA>
; DI void gemm_phase(LAS unsigned char* lds, const Gemm g, const Sched& S, const Epi& E) {
;     ...
;         for (int t = 0; t < nt; t += 2) {
;             const bool last = (t == nt - 2);
;             const char* a1 = cA + (size_t)(t + 1) * kstep;
;             const char* a2 = last ? nA : cA + (size_t)(t + 2) * kstep; const char* b2 = last ? nB : cB + (size_t)(t + 2) * kstep;
;             const char* a3 = a2 + kstep; const char* b3 = b2 + kstep;
;             PG8_KBODY(PG8_WAIT_V(8));
	s_add_i32 s54, s80, s33
	v_lshl_add_u64 v[174:175], v[174:175], 0, s[6:7]
	s_mov_b32 m0, s54
	ds_read_b128 v[190:193], v151 offset:49152
	ds_read_b128 v[194:197], v151 offset:50176
	ds_read_b128 v[198:201], v151 offset:51200
	ds_read_b128 v[202:205], v151 offset:52224
	ds_read_b128 v[206:209], v151 offset:53248
	ds_read_b128 v[214:217], v151 offset:54272
	ds_read_b128 v[218:221], v151 offset:55296
	ds_read_b128 v[222:225], v151 offset:56320
	global_load_lds_dwordx4 v[174:175], off
	s_add_i32 m0, s54, 0x2000
	s_add_u32 s52, s52, 0x40080
	v_lshl_add_u64 v[174:175], v[210:211], 0, s[6:7]
	s_addc_u32 s53, s53, 0
	s_add_i32 s54, s81, s33
	global_load_lds_dwordx4 v[174:175], off
	v_lshl_add_u64 v[174:175], s[52:53], 0, v[132:133]
	s_mov_b32 m0, s54
	s_nop 0
	global_load_lds_dwordx4 v[174:175], off
	v_lshl_add_u64 v[174:175], s[52:53], 0, v[128:129]
	s_add_i32 m0, s54, 0x2000
	s_nop 0
	global_load_lds_dwordx4 v[174:175], off
	v_lshl_add_u64 v[174:175], v[226:227], 0, s[6:7]
	s_mov_b32 m0, s62
	s_nop 0
	global_load_lds_dwordx4 v[174:175], off
	v_lshl_add_u64 v[174:175], v[228:229], 0, s[6:7]
	s_mov_b32 m0, s63
	s_nop 0
	global_load_lds_dwordx4 v[174:175], off
	s_waitcnt vmcnt(8)
	s_waitcnt lgkmcnt(0)
	s_barrier
	s_setprio 1
	s_waitcnt lgkmcnt(0)
	v_mfma_f32_16x16x32_bf16 v[60:63], v[154:157], v[190:193], v[60:63]
	v_mfma_f32_16x16x32_bf16 v[56:59], v[162:165], v[190:193], v[56:59]
	v_mfma_f32_16x16x32_bf16 v[52:55], v[154:157], v[198:201], v[52:55]
	v_mfma_f32_16x16x32_bf16 v[48:51], v[162:165], v[198:201], v[48:51]
	v_mfma_f32_16x16x32_bf16 v[36:39], v[154:157], v[206:209], v[36:39]
	v_mfma_f32_16x16x32_bf16 v[32:35], v[162:165], v[206:209], v[32:35]
	v_mfma_f32_16x16x32_bf16 v[20:23], v[154:157], v[218:221], v[20:23]
	v_mfma_f32_16x16x32_bf16 v[16:19], v[162:165], v[218:221], v[16:19]
	v_mfma_f32_16x16x32_bf16 v[60:63], v[158:161], v[194:197], v[60:63]
	v_mfma_f32_16x16x32_bf16 v[56:59], v[166:169], v[194:197], v[56:59]
	v_mfma_f32_16x16x32_bf16 v[52:55], v[158:161], v[202:205], v[52:55]
	v_mfma_f32_16x16x32_bf16 v[48:51], v[166:169], v[202:205], v[48:51]
	v_mfma_f32_16x16x32_bf16 v[36:39], v[158:161], v[214:217], v[36:39]
	v_mfma_f32_16x16x32_bf16 v[32:35], v[166:169], v[214:217], v[32:35]
	v_mfma_f32_16x16x32_bf16 v[20:23], v[158:161], v[222:225], v[20:23]
	v_mfma_f32_16x16x32_bf16 v[16:19], v[166:169], v[222:225], v[16:19]
	s_setprio 0
	s_setprio 1
	v_mfma_f32_16x16x32_bf16 v[44:47], v[170:173], v[190:193], v[44:47]
	v_mfma_f32_16x16x32_bf16 v[40:43], v[182:185], v[190:193], v[40:43]
	v_mfma_f32_16x16x32_bf16 v[28:31], v[170:173], v[198:201], v[28:31]
	v_mfma_f32_16x16x32_bf16 v[24:27], v[182:185], v[198:201], v[24:27]
	v_mfma_f32_16x16x32_bf16 v[12:15], v[170:173], v[206:209], v[12:15]
	v_mfma_f32_16x16x32_bf16 v[8:11], v[182:185], v[206:209], v[8:11]
	v_mfma_f32_16x16x32_bf16 v[4:7], v[170:173], v[218:221], v[4:7]
	v_mfma_f32_16x16x32_bf16 v[0:3], v[182:185], v[218:221], v[0:3]
	v_mfma_f32_16x16x32_bf16 v[44:47], v[178:181], v[194:197], v[44:47]
	v_mfma_f32_16x16x32_bf16 v[40:43], v[186:189], v[194:197], v[40:43]
	v_mfma_f32_16x16x32_bf16 v[28:31], v[178:181], v[202:205], v[28:31]
	v_mfma_f32_16x16x32_bf16 v[24:27], v[186:189], v[202:205], v[24:27]
	v_mfma_f32_16x16x32_bf16 v[12:15], v[178:181], v[214:217], v[12:15]
	v_mfma_f32_16x16x32_bf16 v[8:11], v[186:189], v[214:217], v[8:11]
	v_mfma_f32_16x16x32_bf16 v[4:7], v[178:181], v[222:225], v[4:7]
	v_mfma_f32_16x16x32_bf16 v[0:3], v[186:189], v[222:225], v[0:3]
	s_setprio 0
	s_barrier
	s_add_i32 s79, s79, 2
	s_add_u32 s46, s46, 0x100
	s_addc_u32 s47, s47, 0
	s_add_u32 s77, s77, 0x100
	s_addc_u32 s78, s78, 0
	s_cmp_gt_u32 s79, 13

;     DI bool next(int i, Unit& u) const { if (!s.next(i >> 1, u)) return false; u.sel = i & 1; return true; }
; #define PG8_WAIT_V(n) asm volatile("s_waitcnt vmcnt(" #n ")" ::: "memory")
; template <class Epi, class Sched, bool ALIGN_EPI, bool CONVA>
; DI void gemm_phase(LAS unsigned char* lds, const Gemm g, const Sched& S, const Epi& E) {
;     const int tid = threadIdx.x, wid = __builtin_amdgcn_readfirstlane(tid >> 6), lane = tid & 63, wr = wid >> 2, wc = wid & 3, fr = lane & 15, fq = lane >> 4;
;     const int K = g.K; const int nt = g.ntk ? g.ntk : K / BK;
;     unsigned voffA[2], voffB[2];
; #pragma unroll
;     for (int i = 0; i < 2; ++i) { int R, C; stage_rc(tid * 16 + i * 8192, R, C); const int Rb = Epi::PERM ? ((R & ~31) + perm32(R & 31)) : R;
;         const int Ra = CONVA ? (128 * (R >> 6) + 8 * (R & 15) + ((R >> 4) & 3)) : R;
;         voffA[i] = (unsigned)(Ra * K + C) * 2u; voffB[i] = (unsigned)(Rb * K + C) * 2u; }
;     const size_t kstep = (size_t)(BK * 2);
;     const size_t hstepB = (size_t)HALF * K * 2, tstepB = 2 * hstepB;
;     const size_t hstepA = CONVA ? (size_t)4 * K * 2 : hstepB, tstepA = CONVA ? (size_t)254 * K * 2 : tstepB;
;     const long abias = CONVA ? -(long)K * 2 : 0;
;     const unsigned ldsw = (unsigned)wid * 1024u;
;     const int aoff = lds_byte(wr * 64 + fr, fq * 8), boff = lds_byte(wc * 32 + fr, fq * 8);
;     ...
;     Unit cur, nxt; int ui = 0;
;     if (!S.next(0, cur)) return;
;     f32x4 acc[2][2][4][2];
; #pragma unroll
;     for (int a = 0; a < 2; ++a)
; #pragma unroll
;         for (int b = 0; b < 2; ++b)
; #pragma unroll
;             for (int m = 0; m < 4; ++m)
; #pragma unroll
;                 for (int n = 0; n < 2; ++n) acc[a][b][m][n] = (f32x4){0.f, 0.f, 0.f, 0.f};
;     bf16x8 At[4][2], B0[2][2], B1[2][2];
;     const char* cA = (const char*)(cur.sel ? g.A2 : g.A) + (size_t)cur.pm * tstepA + abias; const char* cB = (const char*)(cur.sel ? g.Bt2 : g.Bt) + (size_t)cur.pn * tstepB;
;     PG8_STAGE(PG8_SB(0, 0), cB, voffB); PG8_STAGE(PG8_SB(0, 1), cB + hstepB, voffB); PG8_STAGE(PG8_SA(0, 0), cA, voffA); PG8_STAGE(PG8_SA(0, 1), cA + hstepA, voffA);
;     if (wr == 1) PG8_BAR;
;     PG8_WAIT_V(2); PG8_BAR;
;     PG8_STAGE(PG8_SB(1, 0), cB + kstep, voffB); PG8_STAGE(PG8_SA(1, 0), cA + kstep, voffA); PG8_STAGE(PG8_SB(1, 1), cB + hstepB + kstep, voffB);
;     PG8_WAIT_V(6); PG8_BAR;
.LBB0_578:
	s_add_u32 s12, s68, 0xe000000
	s_addc_u32 s13, s69, 0
	s_add_u32 s14, s68, 0x2800000
	s_mov_b64 s[16:17], 0x80
	s_addc_u32 s15, s69, 0
	s_and_b32 s48, s0, 3
	s_add_i32 m0, s7, 0x18000
	v_lshl_add_u64 v[6:7], v[6:7], 0, s[16:17]
	s_lshl_b32 s3, s1, 6
	s_lshl_b32 s18, s1, 13
	s_lshl_b32 s19, s48, 12
	s_waitcnt vmcnt(2)
	s_barrier
	global_load_lds_dwordx4 v[6:7], off
	v_lshl_add_u64 v[4:5], v[4:5], 0, s[16:17]
	s_add_i32 m0, s7, 0x1a000
	s_add_i32 s49, s7, 0x8000
	s_add_i32 s50, s7, 0xa000
	global_load_lds_dwordx4 v[4:5], off
	v_lshl_add_u64 v[2:3], v[2:3], 0, s[16:17]
	s_mov_b32 m0, s49
	s_add_u32 s0, s34, 0x40080
	global_load_lds_dwordx4 v[2:3], off
	v_lshl_add_u64 v[0:1], v[0:1], 0, s[16:17]
	s_mov_b32 m0, s50
	s_addc_u32 s1, s35, 0
	global_load_lds_dwordx4 v[0:1], off
	s_add_i32 m0, s7, 0x1c000
	v_lshl_add_u64 v[0:1], s[0:1], 0, v[180:181]
	global_load_lds_dwordx4 v[0:1], off
	v_lshl_add_u64 v[0:1], s[0:1], 0, v[184:185]
	s_add_i32 m0, s7, 0x1e000
	v_lshlrev_b32_e32 v5, 2, v176
	global_load_lds_dwordx4 v[0:1], off
	v_bfe_u32 v1, v176, 4, 2
	v_and_b32_e32 v0, 15, v176
	v_lshlrev_b32_e32 v3, 4, v1
	v_lshlrev_b32_e32 v6, 6, v176
	s_movk_i32 s0, 0x3c0
	v_lshl_or_b32 v4, v0, 6, v3
	v_and_b32_e32 v5, 32, v5
	v_and_or_b32 v3, v6, s0, v3
	s_cmpk_lt_u32 s2, 0x100
	v_or_b32_e32 v206, s3, v0
	v_bitop3_b32 v4, v4, s18, v5 bitop3:0xde
	v_bitop3_b32 v207, s19, v3, v5 bitop3:0xf6
	s_cselect_b64 s[18:19], -1, 0
	s_add_i32 s2, s3, 0x80
	s_addk_i32 s3, 0xa0
	v_or_b32_e32 v209, s2, v0
	v_or_b32_e32 v211, s3, v0
	v_lshlrev_b32_e32 v0, 8, v176
	v_lshlrev_b32_e32 v2, 3, v1
	v_cmp_eq_u32_e64 s[0:1], 0, v1
	v_and_b32_e32 v0, 0x38000, v0
	v_lshlrev_b32_e32 v1, 11, v10
	v_or3_b32 v0, v8, v0, v1
	v_add_u32_e32 v186, v0, v9
	v_lshlrev_b32_e32 v0, 4, v11
	v_and_b32_e32 v0, 0x78000, v0
	s_waitcnt vmcnt(0)
	v_or3_b32 v0, v8, v0, v1
	v_add_u32_e32 v188, v0, v9
	s_add_i32 s54, 0, 0x10000
	s_add_i32 s55, 0, 0x14000
	v_mbcnt_lo_u32_b32 v0, -1, 0
	v_lshl_or_b32 v208, s48, 5, v2
	v_or_b32_e32 v210, 16, v209
	v_or_b32_e32 v214, 16, v211
	v_or_b32_e32 v215, 48, v209
	s_ashr_i32 s51, s76, 31
	s_ashr_i32 s52, s95, 31
	v_mov_b32_e32 v187, v181
	v_mov_b32_e32 v189, v181
	v_mov_b64_e32 v[190:191], 0x500
	v_mov_b64_e32 v[192:193], 0x4ff
	s_movk_i32 s53, 0xa1
	v_add_u32_e32 v216, s54, v207
	v_add_u32_e32 v217, s55, v207
	v_add_u32_e32 v218, 0, v4
	v_mbcnt_hi_u32_b32 v219, -1, v0
	s_mov_b32 s56, 0
	s_barrier
	s_branch .LBB0_581

;     DI bool next(int i, Unit& u) const { if (!s.next(i >> 1, u)) return false; u.sel = i & 1; return true; }
; template <class Epi, class Sched, bool ALIGN_EPI, bool CONVA>
; DI void gemm_phase(LAS unsigned char* lds, const Gemm g, const Sched& S, const Epi& E) {
;     ...
;         const bool has_next = S.next(ui + 1, nxt);
;         const char* nA = has_next ? (const char*)(nxt.sel ? g.A2 : g.A) + (size_t)nxt.pm * tstepA + abias : cA;
;         const char* nB = has_next ? (const char*)(nxt.sel ? g.Bt2 : g.Bt) + (size_t)nxt.pn * tstepB : cB;
.LBB0_583:
	s_ashr_i32 s25, s24, 31
	s_lshl_b64 s[26:27], s[24:25], 19
	s_add_u32 s26, s33, s26
	s_addc_u32 s27, s42, s27
	s_and_b64 s[28:29], s[2:3], exec
	s_cselect_b32 s25, s27, s31
	s_cselect_b32 s57, s26, s30
	s_ashr_i32 s21, s20, 31
	s_lshl_b64 s[28:29], s[20:21], 19
	s_add_u32 s28, s22, s28
	s_addc_u32 s29, s23, s29
	s_and_b64 s[40:41], s[2:3], exec
	s_cselect_b32 s21, s29, s35
	s_cselect_b32 s58, s28, s34
	s_add_u32 s30, s30, 0x40080
	s_addc_u32 s31, s31, 0
	s_add_u32 s59, s34, 0x100
	s_addc_u32 s60, s35, 0
	s_mov_b32 s61, -2
	s_waitcnt lgkmcnt(0)
	ds_read_b128 v[128:131], v216
	ds_read_b128 v[132:135], v216 offset:1024
	ds_read_b128 v[136:139], v216 offset:2048
	ds_read_b128 v[140:143], v216 offset:3072
	ds_read_b128 v[144:147], v217
	ds_read_b128 v[148:151], v217 offset:1024
	ds_read_b128 v[152:155], v217 offset:2048
	ds_read_b128 v[156:159], v217 offset:3072
	s_add_u32 s34, s30, 0xfffc0080
	s_addc_u32 s35, s31, -1
	s_cmp_eq_u32 s61, 12
	s_cselect_b32 s41, s25, s35
	s_cselect_b32 s40, s57, s34
	s_cselect_b32 s35, s21, s60
	s_cselect_b32 s34, s58, s59
	v_lshl_add_u64 v[224:225], s[30:31], 0, v[186:187]
	s_add_i32 m0, s7, 0xc000
	ds_read_b128 v[160:163], v218
	ds_read_b128 v[164:167], v218 offset:1024
	ds_read_b128 v[168:171], v218 offset:2048
	ds_read_b128 v[172:175], v218 offset:3072
	ds_read_b128 v[194:197], v218 offset:4096
	ds_read_b128 v[198:201], v218 offset:5120
	ds_read_b128 v[202:205], v218 offset:6144
	ds_read_b128 v[220:223], v218 offset:7168
	global_load_lds_dwordx4 v[224:225], off
	v_lshl_add_u64 v[224:225], s[30:31], 0, v[188:189]
	s_add_i32 m0, s7, 0xe000
	s_nop 0
	global_load_lds_dwordx4 v[224:225], off
	s_waitcnt vmcnt(24)
	s_waitcnt lgkmcnt(0)
	s_barrier
	s_setprio 1
	s_waitcnt lgkmcnt(0)
	v_mfma_f32_16x16x32_bf16 v[124:127], v[128:131], v[160:163], 0
	v_mfma_f32_16x16x32_bf16 v[120:123], v[136:139], v[160:163], 0
	v_mfma_f32_16x16x32_bf16 v[108:111], v[128:131], v[168:171], 0
	v_mfma_f32_16x16x32_bf16 v[104:107], v[136:139], v[168:171], 0
	v_mfma_f32_16x16x32_bf16 v[92:95], v[128:131], v[194:197], 0
	v_mfma_f32_16x16x32_bf16 v[88:91], v[136:139], v[194:197], 0
	v_mfma_f32_16x16x32_bf16 v[76:79], v[128:131], v[202:205], 0
	v_mfma_f32_16x16x32_bf16 v[72:75], v[136:139], v[202:205], 0
	v_mfma_f32_16x16x32_bf16 v[124:127], v[132:135], v[164:167], v[124:127]
	v_mfma_f32_16x16x32_bf16 v[120:123], v[140:143], v[164:167], v[120:123]
	v_mfma_f32_16x16x32_bf16 v[108:111], v[132:135], v[172:175], v[108:111]
	v_mfma_f32_16x16x32_bf16 v[104:107], v[140:143], v[172:175], v[104:107]
	v_mfma_f32_16x16x32_bf16 v[92:95], v[132:135], v[198:201], v[92:95]
	v_mfma_f32_16x16x32_bf16 v[88:91], v[140:143], v[198:201], v[88:91]
	v_mfma_f32_16x16x32_bf16 v[76:79], v[132:135], v[220:223], v[76:79]
	v_mfma_f32_16x16x32_bf16 v[72:75], v[140:143], v[220:223], v[72:75]
	s_setprio 0
	s_setprio 1
	v_mfma_f32_16x16x32_bf16 v[116:119], v[144:147], v[160:163], 0
	v_mfma_f32_16x16x32_bf16 v[112:115], v[152:155], v[160:163], 0
	v_mfma_f32_16x16x32_bf16 v[100:103], v[144:147], v[168:171], 0
	v_mfma_f32_16x16x32_bf16 v[96:99], v[152:155], v[168:171], 0
	v_mfma_f32_16x16x32_bf16 v[84:87], v[144:147], v[194:197], 0
	v_mfma_f32_16x16x32_bf16 v[80:83], v[152:155], v[194:197], 0
	v_mfma_f32_16x16x32_bf16 v[68:71], v[144:147], v[202:205], 0
	v_mfma_f32_16x16x32_bf16 v[64:67], v[152:155], v[202:205], 0
	v_mfma_f32_16x16x32_bf16 v[116:119], v[148:151], v[164:167], v[116:119]
	v_mfma_f32_16x16x32_bf16 v[112:115], v[156:159], v[164:167], v[112:115]
	v_mfma_f32_16x16x32_bf16 v[100:103], v[148:151], v[172:175], v[100:103]
	v_mfma_f32_16x16x32_bf16 v[96:99], v[156:159], v[172:175], v[96:99]
	v_mfma_f32_16x16x32_bf16 v[84:87], v[148:151], v[198:201], v[84:87]
	v_mfma_f32_16x16x32_bf16 v[80:83], v[156:159], v[198:201], v[80:83]
	v_mfma_f32_16x16x32_bf16 v[68:71], v[148:151], v[220:223], v[68:71]
	v_mfma_f32_16x16x32_bf16 v[64:67], v[156:159], v[220:223], v[64:67]
	s_setprio 0
	s_barrier
	s_add_i32 s62, s54, s43
	v_lshl_add_u64 v[224:225], s[34:35], 0, v[180:181]
	s_mov_b32 m0, s62
	ds_read_b128 v[160:163], v218 offset:16384
	ds_read_b128 v[164:167], v218 offset:17408
	ds_read_b128 v[168:171], v218 offset:18432
	ds_read_b128 v[172:175], v218 offset:19456
	ds_read_b128 v[194:197], v218 offset:20480
	ds_read_b128 v[198:201], v218 offset:21504
	ds_read_b128 v[202:205], v218 offset:22528
	ds_read_b128 v[220:223], v218 offset:23552
	global_load_lds_dwordx4 v[224:225], off
	s_add_i32 m0, s62, 0x2000
	s_add_u32 s62, s34, 0x40000
	v_lshl_add_u64 v[226:227], s[34:35], 0, v[184:185]
	s_addc_u32 s63, s35, 0
	s_add_i32 s64, s55, s43
	global_load_lds_dwordx4 v[226:227], off
	v_lshl_add_u64 v[228:229], s[62:63], 0, v[180:181]
	s_mov_b32 m0, s64
	v_lshl_add_u64 v[230:231], s[40:41], 0, v[182:183]
	global_load_lds_dwordx4 v[228:229], off
	v_lshl_add_u64 v[228:229], s[62:63], 0, v[184:185]
	s_add_i32 m0, s64, 0x2000
	s_nop 0
	global_load_lds_dwordx4 v[228:229], off
	v_lshl_add_u64 v[228:229], s[40:41], 0, v[178:179]
	s_mov_b32 m0, s7
	s_nop 0
	global_load_lds_dwordx4 v[228:229], off
	s_mov_b32 m0, s44
	s_nop 0
	global_load_lds_dwordx4 v[230:231], off
	s_waitcnt vmcnt(24)
	s_waitcnt lgkmcnt(0)
	s_barrier
	s_setprio 1
	s_waitcnt lgkmcnt(0)
	v_mfma_f32_16x16x32_bf16 v[60:63], v[128:131], v[160:163], 0
	v_mfma_f32_16x16x32_bf16 v[56:59], v[136:139], v[160:163], 0
	v_mfma_f32_16x16x32_bf16 v[44:47], v[128:131], v[168:171], 0
	v_mfma_f32_16x16x32_bf16 v[40:43], v[136:139], v[168:171], 0
	v_mfma_f32_16x16x32_bf16 v[28:31], v[128:131], v[194:197], 0
	v_mfma_f32_16x16x32_bf16 v[24:27], v[136:139], v[194:197], 0
	v_mfma_f32_16x16x32_bf16 v[12:15], v[128:131], v[202:205], 0
	v_mfma_f32_16x16x32_bf16 v[8:11], v[136:139], v[202:205], 0
	v_mfma_f32_16x16x32_bf16 v[60:63], v[132:135], v[164:167], v[60:63]
	v_mfma_f32_16x16x32_bf16 v[56:59], v[140:143], v[164:167], v[56:59]
	v_mfma_f32_16x16x32_bf16 v[44:47], v[132:135], v[172:175], v[44:47]
	v_mfma_f32_16x16x32_bf16 v[40:43], v[140:143], v[172:175], v[40:43]
	v_mfma_f32_16x16x32_bf16 v[28:31], v[132:135], v[198:201], v[28:31]
	v_mfma_f32_16x16x32_bf16 v[24:27], v[140:143], v[198:201], v[24:27]
	v_mfma_f32_16x16x32_bf16 v[12:15], v[132:135], v[220:223], v[12:15]
	v_mfma_f32_16x16x32_bf16 v[8:11], v[140:143], v[220:223], v[8:11]
	s_setprio 0
	s_setprio 1
	v_mfma_f32_16x16x32_bf16 v[52:55], v[144:147], v[160:163], 0
	v_mfma_f32_16x16x32_bf16 v[48:51], v[152:155], v[160:163], 0
	v_mfma_f32_16x16x32_bf16 v[36:39], v[144:147], v[168:171], 0
	v_mfma_f32_16x16x32_bf16 v[32:35], v[152:155], v[168:171], 0
	v_mfma_f32_16x16x32_bf16 v[20:23], v[144:147], v[194:197], 0
	v_mfma_f32_16x16x32_bf16 v[16:19], v[152:155], v[194:197], 0
	v_mfma_f32_16x16x32_bf16 v[4:7], v[144:147], v[202:205], 0
	v_mfma_f32_16x16x32_bf16 v[0:3], v[152:155], v[202:205], 0
	v_mfma_f32_16x16x32_bf16 v[52:55], v[148:151], v[164:167], v[52:55]
	v_mfma_f32_16x16x32_bf16 v[48:51], v[156:159], v[164:167], v[48:51]
	v_mfma_f32_16x16x32_bf16 v[36:39], v[148:151], v[172:175], v[36:39]
	v_mfma_f32_16x16x32_bf16 v[32:35], v[156:159], v[172:175], v[32:35]
	v_mfma_f32_16x16x32_bf16 v[20:23], v[148:151], v[198:201], v[20:23]
	v_mfma_f32_16x16x32_bf16 v[16:19], v[156:159], v[198:201], v[16:19]
	v_mfma_f32_16x16x32_bf16 v[4:7], v[148:151], v[220:223], v[4:7]
	v_mfma_f32_16x16x32_bf16 v[0:3], v[156:159], v[220:223], v[0:3]
	s_setprio 0
	s_barrier
	s_add_i32 s62, 0, 0x18000
	s_add_i32 s63, 0, 0x1c000
	v_add_u32_e32 v140, s62, v207
	v_add_u32_e32 v156, s63, v207
	ds_read_b128 v[128:131], v140
	ds_read_b128 v[132:135], v140 offset:1024
	ds_read_b128 v[136:139], v140 offset:2048
	ds_read_b128 v[140:143], v140 offset:3072
	ds_read_b128 v[144:147], v156
	ds_read_b128 v[148:151], v156 offset:1024
	ds_read_b128 v[152:155], v156 offset:2048
	ds_read_b128 v[156:159], v156 offset:3072
	s_add_u32 s40, s40, 0x40000
	s_addc_u32 s41, s41, 0
	s_mov_b32 m0, s45
	v_lshl_add_u64 v[232:233], s[40:41], 0, v[178:179]
	ds_read_b128 v[160:163], v218 offset:32768
	ds_read_b128 v[164:167], v218 offset:33792
	ds_read_b128 v[168:171], v218 offset:34816
	ds_read_b128 v[172:175], v218 offset:35840
	ds_read_b128 v[194:197], v218 offset:36864
	ds_read_b128 v[198:201], v218 offset:37888
	ds_read_b128 v[202:205], v218 offset:38912
	ds_read_b128 v[220:223], v218 offset:39936
	global_load_lds_dwordx4 v[232:233], off
	v_lshl_add_u64 v[232:233], s[40:41], 0, v[182:183]
	s_mov_b32 m0, s46
	s_nop 0
	global_load_lds_dwordx4 v[232:233], off
	s_waitcnt vmcnt(8)
	s_waitcnt lgkmcnt(0)
	s_barrier
	s_setprio 1
	s_waitcnt lgkmcnt(0)
	v_mfma_f32_16x16x32_bf16 v[124:127], v[128:131], v[160:163], v[124:127]
	v_mfma_f32_16x16x32_bf16 v[120:123], v[136:139], v[160:163], v[120:123]
	v_mfma_f32_16x16x32_bf16 v[108:111], v[128:131], v[168:171], v[108:111]
	v_mfma_f32_16x16x32_bf16 v[104:107], v[136:139], v[168:171], v[104:107]
	v_mfma_f32_16x16x32_bf16 v[92:95], v[128:131], v[194:197], v[92:95]
	v_mfma_f32_16x16x32_bf16 v[88:91], v[136:139], v[194:197], v[88:91]
	v_mfma_f32_16x16x32_bf16 v[76:79], v[128:131], v[202:205], v[76:79]
	v_mfma_f32_16x16x32_bf16 v[72:75], v[136:139], v[202:205], v[72:75]
	v_mfma_f32_16x16x32_bf16 v[124:127], v[132:135], v[164:167], v[124:127]
	v_mfma_f32_16x16x32_bf16 v[120:123], v[140:143], v[164:167], v[120:123]
	v_mfma_f32_16x16x32_bf16 v[108:111], v[132:135], v[172:175], v[108:111]
	v_mfma_f32_16x16x32_bf16 v[104:107], v[140:143], v[172:175], v[104:107]
	v_mfma_f32_16x16x32_bf16 v[92:95], v[132:135], v[198:201], v[92:95]
	v_mfma_f32_16x16x32_bf16 v[88:91], v[140:143], v[198:201], v[88:91]
	v_mfma_f32_16x16x32_bf16 v[76:79], v[132:135], v[220:223], v[76:79]
	v_mfma_f32_16x16x32_bf16 v[72:75], v[140:143], v[220:223], v[72:75]
	s_setprio 0
	s_setprio 1
	v_mfma_f32_16x16x32_bf16 v[116:119], v[144:147], v[160:163], v[116:119]
	v_mfma_f32_16x16x32_bf16 v[112:115], v[152:155], v[160:163], v[112:115]
	v_mfma_f32_16x16x32_bf16 v[100:103], v[144:147], v[168:171], v[100:103]
	v_mfma_f32_16x16x32_bf16 v[96:99], v[152:155], v[168:171], v[96:99]
	v_mfma_f32_16x16x32_bf16 v[84:87], v[144:147], v[194:197], v[84:87]
	v_mfma_f32_16x16x32_bf16 v[80:83], v[152:155], v[194:197], v[80:83]
	v_mfma_f32_16x16x32_bf16 v[68:71], v[144:147], v[202:205], v[68:71]
	v_mfma_f32_16x16x32_bf16 v[64:67], v[152:155], v[202:205], v[64:67]
	v_mfma_f32_16x16x32_bf16 v[116:119], v[148:151], v[164:167], v[116:119]
	v_mfma_f32_16x16x32_bf16 v[112:115], v[156:159], v[164:167], v[112:115]
	v_mfma_f32_16x16x32_bf16 v[100:103], v[148:151], v[172:175], v[100:103]
	v_mfma_f32_16x16x32_bf16 v[96:99], v[156:159], v[172:175], v[96:99]
	v_mfma_f32_16x16x32_bf16 v[84:87], v[148:151], v[198:201], v[84:87]
	v_mfma_f32_16x16x32_bf16 v[80:83], v[156:159], v[198:201], v[80:83]
	v_mfma_f32_16x16x32_bf16 v[68:71], v[148:151], v[220:223], v[68:71]
	v_mfma_f32_16x16x32_bf16 v[64:67], v[156:159], v[220:223], v[64:67]
	s_setprio 0
	s_barrier
; #define PG8_WAIT_V(n) asm volatile("s_waitcnt vmcnt(" #n ")" ::: "memory")
; template <class Epi, class Sched, bool ALIGN_EPI, bool CONVA>
; DI void gemm_phase(LAS unsigned char* lds, const Gemm g, const Sched& S, const Epi& E) {
;     ...
;         for (int t = 0; t < nt; t += 2) {
;             const bool last = (t == nt - 2);
;             const char* a1 = cA + (size_t)(t + 1) * kstep;
;             const char* a2 = last ? nA : cA + (size_t)(t + 2) * kstep; const char* b2 = last ? nB : cB + (size_t)(t + 2) * kstep;
;             const char* a3 = a2 + kstep; const char* b3 = b2 + kstep;
;             PG8_KBODY(PG8_WAIT_V(8));
	s_add_i32 s40, s62, s43
	v_lshl_add_u64 v[224:225], v[224:225], 0, s[16:17]
	s_mov_b32 m0, s40
	ds_read_b128 v[160:163], v218 offset:49152
	ds_read_b128 v[164:167], v218 offset:50176
	ds_read_b128 v[168:171], v218 offset:51200
	ds_read_b128 v[172:175], v218 offset:52224
	ds_read_b128 v[194:197], v218 offset:53248
	ds_read_b128 v[198:201], v218 offset:54272
	ds_read_b128 v[202:205], v218 offset:55296
	ds_read_b128 v[220:223], v218 offset:56320
	global_load_lds_dwordx4 v[224:225], off
	s_add_i32 m0, s40, 0x2000
	s_add_u32 s34, s34, 0x40080
	v_lshl_add_u64 v[224:225], v[226:227], 0, s[16:17]
	s_addc_u32 s35, s35, 0
	s_add_i32 s40, s63, s43
	global_load_lds_dwordx4 v[224:225], off
	v_lshl_add_u64 v[224:225], s[34:35], 0, v[180:181]
	s_mov_b32 m0, s40
	s_nop 0
	global_load_lds_dwordx4 v[224:225], off
	v_lshl_add_u64 v[224:225], s[34:35], 0, v[184:185]
	s_add_i32 m0, s40, 0x2000
	s_nop 0
	global_load_lds_dwordx4 v[224:225], off
	v_lshl_add_u64 v[224:225], v[228:229], 0, s[16:17]
	s_mov_b32 m0, s49
	s_nop 0
	global_load_lds_dwordx4 v[224:225], off
	v_lshl_add_u64 v[224:225], v[230:231], 0, s[16:17]
	s_mov_b32 m0, s50
	s_nop 0
	global_load_lds_dwordx4 v[224:225], off
	s_waitcnt vmcnt(8)
	s_waitcnt lgkmcnt(0)
	s_barrier
	s_setprio 1
	s_waitcnt lgkmcnt(0)
	v_mfma_f32_16x16x32_bf16 v[60:63], v[128:131], v[160:163], v[60:63]
	v_mfma_f32_16x16x32_bf16 v[56:59], v[136:139], v[160:163], v[56:59]
	v_mfma_f32_16x16x32_bf16 v[44:47], v[128:131], v[168:171], v[44:47]
	v_mfma_f32_16x16x32_bf16 v[40:43], v[136:139], v[168:171], v[40:43]
	v_mfma_f32_16x16x32_bf16 v[28:31], v[128:131], v[194:197], v[28:31]
	v_mfma_f32_16x16x32_bf16 v[24:27], v[136:139], v[194:197], v[24:27]
	v_mfma_f32_16x16x32_bf16 v[12:15], v[128:131], v[202:205], v[12:15]
	v_mfma_f32_16x16x32_bf16 v[8:11], v[136:139], v[202:205], v[8:11]
	v_mfma_f32_16x16x32_bf16 v[60:63], v[132:135], v[164:167], v[60:63]
	v_mfma_f32_16x16x32_bf16 v[56:59], v[140:143], v[164:167], v[56:59]
	v_mfma_f32_16x16x32_bf16 v[44:47], v[132:135], v[172:175], v[44:47]
	v_mfma_f32_16x16x32_bf16 v[40:43], v[140:143], v[172:175], v[40:43]
	v_mfma_f32_16x16x32_bf16 v[28:31], v[132:135], v[198:201], v[28:31]
	v_mfma_f32_16x16x32_bf16 v[24:27], v[140:143], v[198:201], v[24:27]
	v_mfma_f32_16x16x32_bf16 v[12:15], v[132:135], v[220:223], v[12:15]
	v_mfma_f32_16x16x32_bf16 v[8:11], v[140:143], v[220:223], v[8:11]
	s_setprio 0
	s_setprio 1
	v_mfma_f32_16x16x32_bf16 v[52:55], v[144:147], v[160:163], v[52:55]
	v_mfma_f32_16x16x32_bf16 v[48:51], v[152:155], v[160:163], v[48:51]
	v_mfma_f32_16x16x32_bf16 v[36:39], v[144:147], v[168:171], v[36:39]
	v_mfma_f32_16x16x32_bf16 v[32:35], v[152:155], v[168:171], v[32:35]
	v_mfma_f32_16x16x32_bf16 v[20:23], v[144:147], v[194:197], v[20:23]
	v_mfma_f32_16x16x32_bf16 v[16:19], v[152:155], v[194:197], v[16:19]
	v_mfma_f32_16x16x32_bf16 v[4:7], v[144:147], v[202:205], v[4:7]
	v_mfma_f32_16x16x32_bf16 v[0:3], v[152:155], v[202:205], v[0:3]
	v_mfma_f32_16x16x32_bf16 v[52:55], v[148:151], v[164:167], v[52:55]
	v_mfma_f32_16x16x32_bf16 v[48:51], v[156:159], v[164:167], v[48:51]
	v_mfma_f32_16x16x32_bf16 v[36:39], v[148:151], v[172:175], v[36:39]
	v_mfma_f32_16x16x32_bf16 v[32:35], v[156:159], v[172:175], v[32:35]
	v_mfma_f32_16x16x32_bf16 v[20:23], v[148:151], v[198:201], v[20:23]
	v_mfma_f32_16x16x32_bf16 v[16:19], v[156:159], v[198:201], v[16:19]
	v_mfma_f32_16x16x32_bf16 v[4:7], v[148:151], v[220:223], v[4:7]
	v_mfma_f32_16x16x32_bf16 v[0:3], v[156:159], v[220:223], v[0:3]
	s_setprio 0
	s_barrier
	s_add_i32 s61, s61, 2
	s_add_u32 s30, s30, 0x100
	s_addc_u32 s31, s31, 0
	s_add_u32 s59, s59, 0x100
	s_addc_u32 s60, s60, 0
	s_cmp_gt_u32 s61, 13

;     DI bool next(int i, Unit& u) const { if (!s.next(i >> 1, u)) return false; u.sel = i & 1; return true; }
; #define PG8_WAIT_V(n) asm volatile("s_waitcnt vmcnt(" #n ")" ::: "memory")
; template <class Epi, class Sched, bool ALIGN_EPI, bool CONVA>
; DI void gemm_phase(LAS unsigned char* lds, const Gemm g, const Sched& S, const Epi& E) {
;     const int tid = threadIdx.x, wid = __builtin_amdgcn_readfirstlane(tid >> 6), lane = tid & 63, wr = wid >> 2, wc = wid & 3, fr = lane & 15, fq = lane >> 4;
;     const int K = g.K; const int nt = g.ntk ? g.ntk : K / BK;
;     unsigned voffA[2], voffB[2];
; #pragma unroll
;     for (int i = 0; i < 2; ++i) { int R, C; stage_rc(tid * 16 + i * 8192, R, C); const int Rb = Epi::PERM ? ((R & ~31) + perm32(R & 31)) : R;
;         const int Ra = CONVA ? (128 * (R >> 6) + 8 * (R & 15) + ((R >> 4) & 3)) : R;
;         voffA[i] = (unsigned)(Ra * K + C) * 2u; voffB[i] = (unsigned)(Rb * K + C) * 2u; }
;     const size_t kstep = (size_t)(BK * 2);
;     const size_t hstepB = (size_t)HALF * K * 2, tstepB = 2 * hstepB;
;     const size_t hstepA = CONVA ? (size_t)4 * K * 2 : hstepB, tstepA = CONVA ? (size_t)254 * K * 2 : tstepB;
;     const long abias = CONVA ? -(long)K * 2 : 0;
;     const unsigned ldsw = (unsigned)wid * 1024u;
;     const int aoff = lds_byte(wr * 64 + fr, fq * 8), boff = lds_byte(wc * 32 + fr, fq * 8);
;     ...
;     Unit cur, nxt; int ui = 0;
;     if (!S.next(0, cur)) return;
;     f32x4 acc[2][2][4][2];
; #pragma unroll
;     for (int a = 0; a < 2; ++a)
; #pragma unroll
;         for (int b = 0; b < 2; ++b)
; #pragma unroll
;             for (int m = 0; m < 4; ++m)
; #pragma unroll
;                 for (int n = 0; n < 2; ++n) acc[a][b][m][n] = (f32x4){0.f, 0.f, 0.f, 0.f};
;     bf16x8 At[4][2], B0[2][2], B1[2][2];
;     const char* cA = (const char*)(cur.sel ? g.A2 : g.A) + (size_t)cur.pm * tstepA + abias; const char* cB = (const char*)(cur.sel ? g.Bt2 : g.Bt) + (size_t)cur.pn * tstepB;
;     PG8_STAGE(PG8_SB(0, 0), cB, voffB); PG8_STAGE(PG8_SB(0, 1), cB + hstepB, voffB); PG8_STAGE(PG8_SA(0, 0), cA, voffA); PG8_STAGE(PG8_SA(0, 1), cA + hstepA, voffA);
;     if (wr == 1) PG8_BAR;
;     PG8_WAIT_V(2); PG8_BAR;
;     PG8_STAGE(PG8_SB(1, 0), cB + kstep, voffB); PG8_STAGE(PG8_SA(1, 0), cA + kstep, voffA); PG8_STAGE(PG8_SB(1, 1), cB + hstepB + kstep, voffB);
;     PG8_WAIT_V(6); PG8_BAR;
.LBB0_711:
	s_add_u32 s12, s68, 0xe000000
	s_addc_u32 s13, s69, 0
	s_add_u32 s14, s68, 0x2800000
	s_mov_b64 s[16:17], 0x80
	s_addc_u32 s15, s69, 0
	s_and_b32 s36, s0, 3
	s_add_i32 m0, s31, 0x18000
	v_lshl_add_u64 v[6:7], v[6:7], 0, s[16:17]
	s_lshl_b32 s3, s1, 6
	s_lshl_b32 s4, s1, 13
	s_lshl_b32 s5, s36, 12
	s_waitcnt vmcnt(2)
	s_barrier
	global_load_lds_dwordx4 v[6:7], off
	v_lshl_add_u64 v[4:5], v[4:5], 0, s[16:17]
	s_add_i32 m0, s31, 0x1a000
	s_add_i32 s37, s31, 0x8000
	s_add_i32 s38, s31, 0xa000
	global_load_lds_dwordx4 v[4:5], off
	v_lshl_add_u64 v[0:1], v[0:1], 0, s[16:17]
	s_mov_b32 m0, s37
	s_add_u32 s0, s24, 0xb0080
	global_load_lds_dwordx4 v[0:1], off
	v_lshl_add_u64 v[0:1], v[2:3], 0, s[16:17]
	s_mov_b32 m0, s38
	s_addc_u32 s1, s25, 0
	global_load_lds_dwordx4 v[0:1], off
	s_add_i32 m0, s31, 0x1c000
	v_lshl_add_u64 v[0:1], s[0:1], 0, v[154:155]
	global_load_lds_dwordx4 v[0:1], off
	v_lshl_add_u64 v[0:1], s[0:1], 0, v[158:159]
	s_add_i32 m0, s31, 0x1e000
	v_bfe_u32 v2, v176, 4, 2
	global_load_lds_dwordx4 v[0:1], off
	v_and_b32_e32 v1, 15, v176
	s_cmpk_lt_u32 s2, 0x100
	v_or_b32_e32 v198, s3, v1
	v_lshlrev_b32_e32 v0, 4, v2
	s_cselect_b64 s[18:19], -1, 0
	s_add_i32 s2, s3, 0x80
	s_addk_i32 s3, 0xa0
	v_lshl_or_b32 v4, v1, 6, v0
	v_lshlrev_b32_e32 v6, 6, v176
	s_movk_i32 s0, 0x3c0
	v_or_b32_e32 v201, s2, v1
	v_or_b32_e32 v203, s3, v1
	v_mov_b32_e32 v1, v155
	v_lshlrev_b32_e32 v5, 2, v176
	v_and_or_b32 v6, v6, s0, v0
	v_lshl_add_u64 v[160:161], s[14:15], 0, v[0:1]
	v_add_u16_e32 v0, v8, v9
	v_and_b32_e32 v5, 32, v5
	s_waitcnt vmcnt(0)
	v_lshrrev_b16_e32 v0, 1, v0
	v_lshlrev_b32_e32 v3, 3, v2
	v_bitop3_b32 v4, v4, s4, v5 bitop3:0xde
	v_bitop3_b32 v199, s5, v6, v5 bitop3:0xf6
	v_add_lshl_u32 v162, v10, v0, 1
	v_add_lshl_u32 v164, v11, v0, 1
	s_add_i32 s42, 0, 0x10000
	s_add_i32 s43, 0, 0x14000
	v_mbcnt_lo_u32_b32 v0, -1, 0
	v_lshl_or_b32 v200, s36, 5, v3
	v_cmp_eq_u32_e64 s[0:1], 0, v2
	v_or_b32_e32 v202, 16, v201
	v_or_b32_e32 v204, 16, v203
	v_cmp_eq_u32_e64 s[2:3], 0, v212
	v_or_b32_e32 v205, 16, v198
	v_or_b32_e32 v206, 32, v198
	v_or_b32_e32 v207, 48, v198
	s_ashr_i32 s39, s76, 31
	s_ashr_i32 s40, s95, 31
	v_mov_b32_e32 v163, v155
	v_mov_b32_e32 v165, v155
	v_mov_b64_e32 v[166:167], 0x500
	v_mov_b64_e32 v[168:169], 0x4ff
	s_movk_i32 s41, 0xa1
	v_add_u32_e32 v208, s42, v199
	v_add_u32_e32 v209, s43, v199
	v_add_u32_e32 v210, 0, v4
	v_mbcnt_hi_u32_b32 v211, -1, v0
	v_mov_b32_e32 v212, 0x358637bd
	s_mov_b32 s44, 0xf800000
	v_mov_b32_e32 v213, 0x260
	s_mov_b32 s45, 0
	s_barrier
	s_branch .LBB0_714

.LBB0_720:
	s_add_u32 s6, s26, 0xb0080
	s_addc_u32 s7, s27, 0
	s_add_u32 s8, s24, 0x100
	s_addc_u32 s50, s25, 0
	s_mov_b32 s51, -2
	ds_read_b128 v[128:131], v208
	ds_read_b128 v[132:135], v208 offset:1024
	ds_read_b128 v[136:139], v208 offset:2048
	ds_read_b128 v[140:143], v208 offset:3072
	ds_read_b128 v[144:147], v209
	ds_read_b128 v[148:151], v209 offset:1024
	ds_read_b128 v[170:173], v209 offset:2048
	ds_read_b128 v[174:177], v209 offset:3072
	s_add_u32 s24, s6, 0xfff50080
	s_addc_u32 s25, s7, -1
	s_cmp_eq_u32 s51, 40
	s_cselect_b32 s27, s21, s25
	s_cselect_b32 s26, s20, s24
	s_cselect_b32 s25, s23, s50
	s_cselect_b32 s24, s22, s8
	v_lshl_add_u64 v[226:227], s[6:7], 0, v[162:163]
	s_add_i32 m0, s31, 0xc000
	ds_read_b128 v[178:181], v210
	ds_read_b128 v[182:185], v210 offset:1024
	ds_read_b128 v[186:189], v210 offset:2048
	ds_read_b128 v[190:193], v210 offset:3072
	ds_read_b128 v[194:197], v210 offset:4096
	ds_read_b128 v[214:217], v210 offset:5120
	ds_read_b128 v[218:221], v210 offset:6144
	ds_read_b128 v[222:225], v210 offset:7168
	global_load_lds_dwordx4 v[226:227], off
	v_lshl_add_u64 v[226:227], s[6:7], 0, v[164:165]
	s_add_i32 m0, s31, 0xe000
	s_nop 0
	global_load_lds_dwordx4 v[226:227], off
	s_waitcnt vmcnt(40)
	s_waitcnt lgkmcnt(0)
	s_barrier
	s_setprio 1
	s_waitcnt lgkmcnt(0)
	v_mfma_f32_16x16x32_bf16 v[124:127], v[128:131], v[178:181], 0
	v_mfma_f32_16x16x32_bf16 v[120:123], v[136:139], v[178:181], 0
	v_mfma_f32_16x16x32_bf16 v[108:111], v[128:131], v[186:189], 0
	v_mfma_f32_16x16x32_bf16 v[104:107], v[136:139], v[186:189], 0
	v_mfma_f32_16x16x32_bf16 v[92:95], v[128:131], v[194:197], 0
	v_mfma_f32_16x16x32_bf16 v[88:91], v[136:139], v[194:197], 0
	v_mfma_f32_16x16x32_bf16 v[76:79], v[128:131], v[218:221], 0
	v_mfma_f32_16x16x32_bf16 v[72:75], v[136:139], v[218:221], 0
	v_mfma_f32_16x16x32_bf16 v[124:127], v[132:135], v[182:185], v[124:127]
	v_mfma_f32_16x16x32_bf16 v[120:123], v[140:143], v[182:185], v[120:123]
	v_mfma_f32_16x16x32_bf16 v[108:111], v[132:135], v[190:193], v[108:111]
	v_mfma_f32_16x16x32_bf16 v[104:107], v[140:143], v[190:193], v[104:107]
	v_mfma_f32_16x16x32_bf16 v[92:95], v[132:135], v[214:217], v[92:95]
	v_mfma_f32_16x16x32_bf16 v[88:91], v[140:143], v[214:217], v[88:91]
	v_mfma_f32_16x16x32_bf16 v[76:79], v[132:135], v[222:225], v[76:79]
	v_mfma_f32_16x16x32_bf16 v[72:75], v[140:143], v[222:225], v[72:75]
	s_setprio 0
	s_setprio 1
	v_mfma_f32_16x16x32_bf16 v[116:119], v[144:147], v[178:181], 0
	v_mfma_f32_16x16x32_bf16 v[112:115], v[170:173], v[178:181], 0
	v_mfma_f32_16x16x32_bf16 v[100:103], v[144:147], v[186:189], 0
	v_mfma_f32_16x16x32_bf16 v[96:99], v[170:173], v[186:189], 0
	v_mfma_f32_16x16x32_bf16 v[84:87], v[144:147], v[194:197], 0
	v_mfma_f32_16x16x32_bf16 v[80:83], v[170:173], v[194:197], 0
	v_mfma_f32_16x16x32_bf16 v[68:71], v[144:147], v[218:221], 0
	v_mfma_f32_16x16x32_bf16 v[64:67], v[170:173], v[218:221], 0
	v_mfma_f32_16x16x32_bf16 v[116:119], v[148:151], v[182:185], v[116:119]
	v_mfma_f32_16x16x32_bf16 v[112:115], v[174:177], v[182:185], v[112:115]
	v_mfma_f32_16x16x32_bf16 v[100:103], v[148:151], v[190:193], v[100:103]
	v_mfma_f32_16x16x32_bf16 v[96:99], v[174:177], v[190:193], v[96:99]
	v_mfma_f32_16x16x32_bf16 v[84:87], v[148:151], v[214:217], v[84:87]
	v_mfma_f32_16x16x32_bf16 v[80:83], v[174:177], v[214:217], v[80:83]
	v_mfma_f32_16x16x32_bf16 v[68:71], v[148:151], v[222:225], v[68:71]
	v_mfma_f32_16x16x32_bf16 v[64:67], v[174:177], v[222:225], v[64:67]
	s_setprio 0
	s_barrier
	s_add_i32 s52, s42, s30
	v_lshl_add_u64 v[226:227], s[24:25], 0, v[154:155]
	s_mov_b32 m0, s52
	ds_read_b128 v[178:181], v210 offset:16384
	ds_read_b128 v[182:185], v210 offset:17408
	ds_read_b128 v[186:189], v210 offset:18432
	ds_read_b128 v[190:193], v210 offset:19456
	ds_read_b128 v[194:197], v210 offset:20480
	ds_read_b128 v[214:217], v210 offset:21504
	ds_read_b128 v[218:221], v210 offset:22528
	ds_read_b128 v[222:225], v210 offset:23552
	global_load_lds_dwordx4 v[226:227], off
	s_add_i32 m0, s52, 0x2000
	s_add_u32 s52, s24, 0xb0000
	v_lshl_add_u64 v[228:229], s[24:25], 0, v[158:159]
	s_addc_u32 s53, s25, 0
	s_add_i32 s54, s43, s30
	global_load_lds_dwordx4 v[228:229], off
	v_lshl_add_u64 v[230:231], s[52:53], 0, v[154:155]
	s_mov_b32 m0, s54
	v_lshl_add_u64 v[232:233], s[26:27], 0, v[156:157]
	global_load_lds_dwordx4 v[230:231], off
	v_lshl_add_u64 v[230:231], s[52:53], 0, v[158:159]
	s_add_i32 m0, s54, 0x2000
	s_nop 0
	global_load_lds_dwordx4 v[230:231], off
	v_lshl_add_u64 v[230:231], s[26:27], 0, v[152:153]
	s_mov_b32 m0, s31
	s_nop 0
	global_load_lds_dwordx4 v[230:231], off
	s_mov_b32 m0, s33
	s_nop 0
	global_load_lds_dwordx4 v[232:233], off
	s_waitcnt vmcnt(40)
	s_waitcnt lgkmcnt(0)
	s_barrier
	s_setprio 1
	s_waitcnt lgkmcnt(0)
	v_mfma_f32_16x16x32_bf16 v[60:63], v[128:131], v[178:181], 0
	v_mfma_f32_16x16x32_bf16 v[56:59], v[136:139], v[178:181], 0
	v_mfma_f32_16x16x32_bf16 v[44:47], v[128:131], v[186:189], 0
	v_mfma_f32_16x16x32_bf16 v[40:43], v[136:139], v[186:189], 0
	v_mfma_f32_16x16x32_bf16 v[28:31], v[128:131], v[194:197], 0
	v_mfma_f32_16x16x32_bf16 v[24:27], v[136:139], v[194:197], 0
	v_mfma_f32_16x16x32_bf16 v[12:15], v[128:131], v[218:221], 0
	v_mfma_f32_16x16x32_bf16 v[8:11], v[136:139], v[218:221], 0
	v_mfma_f32_16x16x32_bf16 v[60:63], v[132:135], v[182:185], v[60:63]
	v_mfma_f32_16x16x32_bf16 v[56:59], v[140:143], v[182:185], v[56:59]
	v_mfma_f32_16x16x32_bf16 v[44:47], v[132:135], v[190:193], v[44:47]
	v_mfma_f32_16x16x32_bf16 v[40:43], v[140:143], v[190:193], v[40:43]
	v_mfma_f32_16x16x32_bf16 v[28:31], v[132:135], v[214:217], v[28:31]
	v_mfma_f32_16x16x32_bf16 v[24:27], v[140:143], v[214:217], v[24:27]
	v_mfma_f32_16x16x32_bf16 v[12:15], v[132:135], v[222:225], v[12:15]
	v_mfma_f32_16x16x32_bf16 v[8:11], v[140:143], v[222:225], v[8:11]
	s_setprio 0
	s_setprio 1
	v_mfma_f32_16x16x32_bf16 v[52:55], v[144:147], v[178:181], 0
	v_mfma_f32_16x16x32_bf16 v[48:51], v[170:173], v[178:181], 0
	v_mfma_f32_16x16x32_bf16 v[36:39], v[144:147], v[186:189], 0
	v_mfma_f32_16x16x32_bf16 v[32:35], v[170:173], v[186:189], 0
	v_mfma_f32_16x16x32_bf16 v[20:23], v[144:147], v[194:197], 0
	v_mfma_f32_16x16x32_bf16 v[16:19], v[170:173], v[194:197], 0
	v_mfma_f32_16x16x32_bf16 v[4:7], v[144:147], v[218:221], 0
	v_mfma_f32_16x16x32_bf16 v[0:3], v[170:173], v[218:221], 0
	v_mfma_f32_16x16x32_bf16 v[52:55], v[148:151], v[182:185], v[52:55]
	v_mfma_f32_16x16x32_bf16 v[48:51], v[174:177], v[182:185], v[48:51]
	v_mfma_f32_16x16x32_bf16 v[36:39], v[148:151], v[190:193], v[36:39]
	v_mfma_f32_16x16x32_bf16 v[32:35], v[174:177], v[190:193], v[32:35]
	v_mfma_f32_16x16x32_bf16 v[20:23], v[148:151], v[214:217], v[20:23]
	v_mfma_f32_16x16x32_bf16 v[16:19], v[174:177], v[214:217], v[16:19]
	v_mfma_f32_16x16x32_bf16 v[4:7], v[148:151], v[222:225], v[4:7]
	v_mfma_f32_16x16x32_bf16 v[0:3], v[174:177], v[222:225], v[0:3]
	s_setprio 0
	s_barrier
	s_add_i32 s52, 0, 0x18000
	s_add_i32 s53, 0, 0x1c000
	v_add_u32_e32 v140, s52, v199
	v_add_u32_e32 v174, s53, v199
	ds_read_b128 v[128:131], v140
	ds_read_b128 v[132:135], v140 offset:1024
	ds_read_b128 v[136:139], v140 offset:2048
	ds_read_b128 v[140:143], v140 offset:3072
	ds_read_b128 v[144:147], v174
	ds_read_b128 v[148:151], v174 offset:1024
	ds_read_b128 v[170:173], v174 offset:2048
	ds_read_b128 v[174:177], v174 offset:3072
	s_add_u32 s26, s26, 0xb0000
	s_addc_u32 s27, s27, 0
	s_mov_b32 m0, s34
	v_lshl_add_u64 v[234:235], s[26:27], 0, v[152:153]
	ds_read_b128 v[178:181], v210 offset:32768
	ds_read_b128 v[182:185], v210 offset:33792
	ds_read_b128 v[186:189], v210 offset:34816
	ds_read_b128 v[190:193], v210 offset:35840
	ds_read_b128 v[194:197], v210 offset:36864
	ds_read_b128 v[214:217], v210 offset:37888
	ds_read_b128 v[218:221], v210 offset:38912
	ds_read_b128 v[222:225], v210 offset:39936
	global_load_lds_dwordx4 v[234:235], off
	v_lshl_add_u64 v[234:235], s[26:27], 0, v[156:157]
	s_mov_b32 m0, s35
	s_nop 0
	global_load_lds_dwordx4 v[234:235], off
	s_waitcnt vmcnt(8)
	s_waitcnt lgkmcnt(0)
	s_barrier
	s_setprio 1
	s_waitcnt lgkmcnt(0)
	v_mfma_f32_16x16x32_bf16 v[124:127], v[128:131], v[178:181], v[124:127]
	v_mfma_f32_16x16x32_bf16 v[120:123], v[136:139], v[178:181], v[120:123]
	v_mfma_f32_16x16x32_bf16 v[108:111], v[128:131], v[186:189], v[108:111]
	v_mfma_f32_16x16x32_bf16 v[104:107], v[136:139], v[186:189], v[104:107]
	v_mfma_f32_16x16x32_bf16 v[92:95], v[128:131], v[194:197], v[92:95]
	v_mfma_f32_16x16x32_bf16 v[88:91], v[136:139], v[194:197], v[88:91]
	v_mfma_f32_16x16x32_bf16 v[76:79], v[128:131], v[218:221], v[76:79]
	v_mfma_f32_16x16x32_bf16 v[72:75], v[136:139], v[218:221], v[72:75]
	v_mfma_f32_16x16x32_bf16 v[124:127], v[132:135], v[182:185], v[124:127]
	v_mfma_f32_16x16x32_bf16 v[120:123], v[140:143], v[182:185], v[120:123]
	v_mfma_f32_16x16x32_bf16 v[108:111], v[132:135], v[190:193], v[108:111]
	v_mfma_f32_16x16x32_bf16 v[104:107], v[140:143], v[190:193], v[104:107]
	v_mfma_f32_16x16x32_bf16 v[92:95], v[132:135], v[214:217], v[92:95]
	v_mfma_f32_16x16x32_bf16 v[88:91], v[140:143], v[214:217], v[88:91]
	v_mfma_f32_16x16x32_bf16 v[76:79], v[132:135], v[222:225], v[76:79]
	v_mfma_f32_16x16x32_bf16 v[72:75], v[140:143], v[222:225], v[72:75]
	s_setprio 0
	s_setprio 1
	v_mfma_f32_16x16x32_bf16 v[116:119], v[144:147], v[178:181], v[116:119]
	v_mfma_f32_16x16x32_bf16 v[112:115], v[170:173], v[178:181], v[112:115]
	v_mfma_f32_16x16x32_bf16 v[100:103], v[144:147], v[186:189], v[100:103]
	v_mfma_f32_16x16x32_bf16 v[96:99], v[170:173], v[186:189], v[96:99]
	v_mfma_f32_16x16x32_bf16 v[84:87], v[144:147], v[194:197], v[84:87]
	v_mfma_f32_16x16x32_bf16 v[80:83], v[170:173], v[194:197], v[80:83]
	v_mfma_f32_16x16x32_bf16 v[68:71], v[144:147], v[218:221], v[68:71]
	v_mfma_f32_16x16x32_bf16 v[64:67], v[170:173], v[218:221], v[64:67]
	v_mfma_f32_16x16x32_bf16 v[116:119], v[148:151], v[182:185], v[116:119]
	v_mfma_f32_16x16x32_bf16 v[112:115], v[174:177], v[182:185], v[112:115]
	v_mfma_f32_16x16x32_bf16 v[100:103], v[148:151], v[190:193], v[100:103]
	v_mfma_f32_16x16x32_bf16 v[96:99], v[174:177], v[190:193], v[96:99]
	v_mfma_f32_16x16x32_bf16 v[84:87], v[148:151], v[214:217], v[84:87]
	v_mfma_f32_16x16x32_bf16 v[80:83], v[174:177], v[214:217], v[80:83]
	v_mfma_f32_16x16x32_bf16 v[68:71], v[148:151], v[222:225], v[68:71]
	v_mfma_f32_16x16x32_bf16 v[64:67], v[174:177], v[222:225], v[64:67]
	s_setprio 0
	s_barrier
; #define PG8_WAIT_V(n) asm volatile("s_waitcnt vmcnt(" #n ")" ::: "memory")
; template <class Epi, class Sched, bool ALIGN_EPI, bool CONVA>
; DI void gemm_phase(LAS unsigned char* lds, const Gemm g, const Sched& S, const Epi& E) {
;     ...
;         for (int t = 0; t < nt; t += 2) {
;             const bool last = (t == nt - 2);
;             const char* a1 = cA + (size_t)(t + 1) * kstep;
;             const char* a2 = last ? nA : cA + (size_t)(t + 2) * kstep; const char* b2 = last ? nB : cB + (size_t)(t + 2) * kstep;
;             const char* a3 = a2 + kstep; const char* b3 = b2 + kstep;
;             PG8_KBODY(PG8_WAIT_V(8));
	s_add_i32 s26, s52, s30
	v_lshl_add_u64 v[226:227], v[226:227], 0, s[16:17]
	s_mov_b32 m0, s26
	ds_read_b128 v[178:181], v210 offset:49152
	ds_read_b128 v[182:185], v210 offset:50176
	ds_read_b128 v[186:189], v210 offset:51200
	ds_read_b128 v[190:193], v210 offset:52224
	ds_read_b128 v[194:197], v210 offset:53248
	ds_read_b128 v[214:217], v210 offset:54272
	ds_read_b128 v[218:221], v210 offset:55296
	ds_read_b128 v[222:225], v210 offset:56320
	global_load_lds_dwordx4 v[226:227], off
	s_add_i32 m0, s26, 0x2000
	s_add_u32 s24, s24, 0xb0080
	v_lshl_add_u64 v[226:227], v[228:229], 0, s[16:17]
	s_addc_u32 s25, s25, 0
	s_add_i32 s26, s53, s30
	global_load_lds_dwordx4 v[226:227], off
	v_lshl_add_u64 v[226:227], s[24:25], 0, v[154:155]
	s_mov_b32 m0, s26
	s_nop 0
	global_load_lds_dwordx4 v[226:227], off
	v_lshl_add_u64 v[226:227], s[24:25], 0, v[158:159]
	s_add_i32 m0, s26, 0x2000
	s_nop 0
	global_load_lds_dwordx4 v[226:227], off
	v_lshl_add_u64 v[226:227], v[230:231], 0, s[16:17]
	s_mov_b32 m0, s37
	s_nop 0
	global_load_lds_dwordx4 v[226:227], off
	v_lshl_add_u64 v[226:227], v[232:233], 0, s[16:17]
	s_mov_b32 m0, s38
	s_nop 0
	global_load_lds_dwordx4 v[226:227], off
	s_waitcnt vmcnt(8)
	s_waitcnt lgkmcnt(0)
	s_barrier
	s_setprio 1
	s_waitcnt lgkmcnt(0)
	v_mfma_f32_16x16x32_bf16 v[60:63], v[128:131], v[178:181], v[60:63]
	v_mfma_f32_16x16x32_bf16 v[56:59], v[136:139], v[178:181], v[56:59]
	v_mfma_f32_16x16x32_bf16 v[44:47], v[128:131], v[186:189], v[44:47]
	v_mfma_f32_16x16x32_bf16 v[40:43], v[136:139], v[186:189], v[40:43]
	v_mfma_f32_16x16x32_bf16 v[28:31], v[128:131], v[194:197], v[28:31]
	v_mfma_f32_16x16x32_bf16 v[24:27], v[136:139], v[194:197], v[24:27]
	v_mfma_f32_16x16x32_bf16 v[12:15], v[128:131], v[218:221], v[12:15]
	v_mfma_f32_16x16x32_bf16 v[8:11], v[136:139], v[218:221], v[8:11]
	v_mfma_f32_16x16x32_bf16 v[60:63], v[132:135], v[182:185], v[60:63]
	v_mfma_f32_16x16x32_bf16 v[56:59], v[140:143], v[182:185], v[56:59]
	v_mfma_f32_16x16x32_bf16 v[44:47], v[132:135], v[190:193], v[44:47]
	v_mfma_f32_16x16x32_bf16 v[40:43], v[140:143], v[190:193], v[40:43]
	v_mfma_f32_16x16x32_bf16 v[28:31], v[132:135], v[214:217], v[28:31]
	v_mfma_f32_16x16x32_bf16 v[24:27], v[140:143], v[214:217], v[24:27]
	v_mfma_f32_16x16x32_bf16 v[12:15], v[132:135], v[222:225], v[12:15]
	v_mfma_f32_16x16x32_bf16 v[8:11], v[140:143], v[222:225], v[8:11]
	s_setprio 0
	s_setprio 1
	v_mfma_f32_16x16x32_bf16 v[52:55], v[144:147], v[178:181], v[52:55]
	v_mfma_f32_16x16x32_bf16 v[48:51], v[170:173], v[178:181], v[48:51]
	v_mfma_f32_16x16x32_bf16 v[36:39], v[144:147], v[186:189], v[36:39]
	v_mfma_f32_16x16x32_bf16 v[32:35], v[170:173], v[186:189], v[32:35]
	v_mfma_f32_16x16x32_bf16 v[20:23], v[144:147], v[194:197], v[20:23]
	v_mfma_f32_16x16x32_bf16 v[16:19], v[170:173], v[194:197], v[16:19]
	v_mfma_f32_16x16x32_bf16 v[4:7], v[144:147], v[218:221], v[4:7]
	v_mfma_f32_16x16x32_bf16 v[0:3], v[170:173], v[218:221], v[0:3]
	v_mfma_f32_16x16x32_bf16 v[52:55], v[148:151], v[182:185], v[52:55]
	v_mfma_f32_16x16x32_bf16 v[48:51], v[174:177], v[182:185], v[48:51]
	v_mfma_f32_16x16x32_bf16 v[36:39], v[148:151], v[190:193], v[36:39]
	v_mfma_f32_16x16x32_bf16 v[32:35], v[174:177], v[190:193], v[32:35]
	v_mfma_f32_16x16x32_bf16 v[20:23], v[148:151], v[214:217], v[20:23]
	v_mfma_f32_16x16x32_bf16 v[16:19], v[174:177], v[214:217], v[16:19]
	v_mfma_f32_16x16x32_bf16 v[4:7], v[148:151], v[222:225], v[4:7]
	v_mfma_f32_16x16x32_bf16 v[0:3], v[174:177], v[222:225], v[0:3]
	s_setprio 0
	s_barrier
	s_add_i32 s51, s51, 2
	s_add_u32 s6, s6, 0x100
	s_addc_u32 s7, s7, 0
	s_add_u32 s8, s8, 0x100
	s_addc_u32 s50, s50, 0
	s_cmp_gt_u32 s51, 41
